# HGRN intra-chunk decay attention: product-sum of the four exp terms done as an f32 FMA chain into the accumulator instead of packed multiply plus add tree
# speedup vs baseline: 1.0012x; 1.0012x over previous
; DI float ex2(float x) { return __builtin_amdgcn_exp2f(x); }
; DI void hgrn_h3(const Params& p, int l, int item, char* lds) {
;     ...
;     for (int d4 = 0; d4 < 16; ++d4) {
;       const f32x4 q4 = *(const f32x4*)(QS + t * HP + 4 * d4), b4 = *(const f32x4*)(B2 + t * HP + 4 * d4);
; #pragma unroll
;       for (int j = 0; j < 16; ++j) {
;         if (j < jcount) {
;           const f32x4 l4 = *(const f32x4*)(LK + (sq + 4 * j) * HP + 4 * d4);
;           at[j] += q4.x * ex2(b4.x + l4.x) + q4.y * ex2(b4.y + l4.y) + q4.z * ex2(b4.z + l4.z) + q4.w * ex2(b4.w + l4.w);
;         }
;       }
.LBB0_631:
	ds_read_b128 v[38:41], v36 offset:4352
	s_waitcnt lgkmcnt(0)
	v_add_f32_e32 v37, v16, v38
	v_add_f32_e32 v39, v17, v39
	v_add_f32_e32 v40, v18, v40
	v_exp_f32_e32 v38, v37
	v_exp_f32_e32 v39, v39
	v_add_f32_e32 v37, v19, v41
	v_exp_f32_e32 v40, v40
	v_exp_f32_e32 v41, v37
	v_fmac_f32_e32 v4, v20, v38
	v_fmac_f32_e32 v4, v21, v39
	v_fmac_f32_e32 v4, v22, v40
	v_fmac_f32_e32 v4, v23, v41
	s_or_b64 exec, exec, s[2:3]
	s_and_saveexec_b64 s[2:3], vcc
	s_cbranch_execz .LBB0_621
.LBB0_632:
	ds_read_b128 v[38:41], v36 offset:5440
	s_waitcnt lgkmcnt(0)
	v_add_f32_e32 v37, v16, v38
	v_add_f32_e32 v39, v17, v39
	v_add_f32_e32 v40, v18, v40
	v_exp_f32_e32 v38, v37
	v_exp_f32_e32 v39, v39
	v_add_f32_e32 v37, v19, v41
	v_exp_f32_e32 v40, v40
	v_exp_f32_e32 v41, v37
	v_fmac_f32_e32 v5, v20, v38
	v_fmac_f32_e32 v5, v21, v39
	v_fmac_f32_e32 v5, v22, v40
	v_fmac_f32_e32 v5, v23, v41
	s_or_b64 exec, exec, s[2:3]
	s_and_saveexec_b64 s[2:3], vcc
	s_cbranch_execz .LBB0_622
.LBB0_633:
	ds_read_b128 v[38:41], v36 offset:6528
	s_waitcnt lgkmcnt(0)
	v_add_f32_e32 v37, v16, v38
	v_add_f32_e32 v39, v17, v39
	v_add_f32_e32 v40, v18, v40
	v_exp_f32_e32 v38, v37
	v_exp_f32_e32 v39, v39
	v_add_f32_e32 v37, v19, v41
	v_exp_f32_e32 v40, v40
	v_exp_f32_e32 v41, v37
	v_fmac_f32_e32 v6, v20, v38
	v_fmac_f32_e32 v6, v21, v39
	v_fmac_f32_e32 v6, v22, v40
	v_fmac_f32_e32 v6, v23, v41
	s_or_b64 exec, exec, s[2:3]
	s_and_saveexec_b64 s[2:3], vcc
	s_cbranch_execz .LBB0_623
.LBB0_634:
	ds_read_b128 v[38:41], v36 offset:7616
	s_waitcnt lgkmcnt(0)
	v_add_f32_e32 v37, v16, v38
	v_add_f32_e32 v39, v17, v39
	v_add_f32_e32 v40, v18, v40
	v_exp_f32_e32 v38, v37
	v_exp_f32_e32 v39, v39
	v_add_f32_e32 v37, v19, v41
	v_exp_f32_e32 v40, v40
	v_exp_f32_e32 v41, v37
	v_fmac_f32_e32 v7, v20, v38
	v_fmac_f32_e32 v7, v21, v39
	v_fmac_f32_e32 v7, v22, v40
	v_fmac_f32_e32 v7, v23, v41
	s_or_b64 exec, exec, s[2:3]
	s_and_saveexec_b64 s[2:3], s[0:1]
	s_cbranch_execz .LBB0_624
.LBB0_635:
	ds_read_b128 v[38:41], v36 offset:8704
	s_waitcnt lgkmcnt(0)
	v_add_f32_e32 v37, v16, v38
	v_add_f32_e32 v39, v17, v39
	v_add_f32_e32 v40, v18, v40
	v_exp_f32_e32 v38, v37
	v_exp_f32_e32 v39, v39
	v_add_f32_e32 v37, v19, v41
	v_exp_f32_e32 v40, v40
	v_exp_f32_e32 v41, v37
	v_fmac_f32_e32 v8, v20, v38
	v_fmac_f32_e32 v8, v21, v39
	v_fmac_f32_e32 v8, v22, v40
	v_fmac_f32_e32 v8, v23, v41
	s_or_b64 exec, exec, s[2:3]
	s_and_saveexec_b64 s[2:3], s[44:45]
	s_cbranch_execz .LBB0_625
.LBB0_636:
	ds_read_b128 v[38:41], v36 offset:9792
	s_waitcnt lgkmcnt(0)
	v_add_f32_e32 v37, v16, v38
	v_add_f32_e32 v39, v17, v39
	v_add_f32_e32 v40, v18, v40
	v_exp_f32_e32 v38, v37
	v_exp_f32_e32 v39, v39
	v_add_f32_e32 v37, v19, v41
	v_exp_f32_e32 v40, v40
	v_exp_f32_e32 v41, v37
	v_fmac_f32_e32 v9, v20, v38
	v_fmac_f32_e32 v9, v21, v39
	v_fmac_f32_e32 v9, v22, v40
	v_fmac_f32_e32 v9, v23, v41
	s_or_b64 exec, exec, s[2:3]
	s_and_saveexec_b64 s[2:3], s[46:47]
	s_cbranch_execz .LBB0_626
.LBB0_637:
	ds_read_b128 v[38:41], v36 offset:10880
	s_waitcnt lgkmcnt(0)
	v_add_f32_e32 v37, v16, v38
	v_add_f32_e32 v39, v17, v39
	v_add_f32_e32 v40, v18, v40
	v_exp_f32_e32 v38, v37
	v_exp_f32_e32 v39, v39
	v_add_f32_e32 v37, v19, v41
	v_exp_f32_e32 v40, v40
	v_exp_f32_e32 v41, v37
	v_fmac_f32_e32 v10, v20, v38
	v_fmac_f32_e32 v10, v21, v39
	v_fmac_f32_e32 v10, v22, v40
	v_fmac_f32_e32 v10, v23, v41
	s_or_b64 exec, exec, s[2:3]
	s_and_saveexec_b64 s[2:3], s[0:1]
	s_cbranch_execz .LBB0_627
.LBB0_638:
	ds_read_b128 v[38:41], v36 offset:11968
	s_waitcnt lgkmcnt(0)
	v_add_f32_e32 v37, v16, v38
	v_add_f32_e32 v39, v17, v39
	v_add_f32_e32 v40, v18, v40
	v_exp_f32_e32 v38, v37
	v_exp_f32_e32 v39, v39
	v_add_f32_e32 v37, v19, v41
	v_exp_f32_e32 v40, v40
	v_exp_f32_e32 v41, v37
	v_fmac_f32_e32 v11, v20, v38
	v_fmac_f32_e32 v11, v21, v39
	v_fmac_f32_e32 v11, v22, v40
	v_fmac_f32_e32 v11, v23, v41
	s_or_b64 exec, exec, s[2:3]
	s_and_saveexec_b64 s[2:3], s[48:49]
	s_cbranch_execz .LBB0_628
.LBB0_639:
	ds_read_b128 v[38:41], v36 offset:13056
	s_waitcnt lgkmcnt(0)
	v_add_f32_e32 v37, v16, v38
	v_add_f32_e32 v39, v17, v39
	v_add_f32_e32 v40, v18, v40
	v_exp_f32_e32 v38, v37
	v_exp_f32_e32 v39, v39
	v_add_f32_e32 v37, v19, v41
	v_exp_f32_e32 v40, v40
	v_exp_f32_e32 v41, v37
	v_fmac_f32_e32 v12, v20, v38
	v_fmac_f32_e32 v12, v21, v39
	v_fmac_f32_e32 v12, v22, v40
	v_fmac_f32_e32 v12, v23, v41
	s_or_b64 exec, exec, s[2:3]
	s_and_saveexec_b64 s[2:3], s[50:51]
	s_cbranch_execz .LBB0_629
.LBB0_640:
	ds_read_b128 v[38:41], v36 offset:14144
	s_waitcnt lgkmcnt(0)
	v_add_f32_e32 v37, v16, v38
	v_add_f32_e32 v39, v17, v39
	v_add_f32_e32 v40, v18, v40
	v_exp_f32_e32 v38, v37
	v_exp_f32_e32 v39, v39
	v_add_f32_e32 v37, v19, v41
	v_exp_f32_e32 v40, v40
	v_exp_f32_e32 v41, v37
	v_fmac_f32_e32 v13, v20, v38
	v_fmac_f32_e32 v13, v21, v39
	v_fmac_f32_e32 v13, v22, v40
	v_fmac_f32_e32 v13, v23, v41
	s_or_b64 exec, exec, s[2:3]
	s_and_saveexec_b64 s[2:3], s[52:53]
	s_cbranch_execz .LBB0_630
.LBB0_641:
	ds_read_b128 v[38:41], v36 offset:15232
	s_waitcnt lgkmcnt(0)
	v_add_f32_e32 v37, v16, v38
	v_add_f32_e32 v39, v17, v39
	v_add_f32_e32 v40, v18, v40
	v_exp_f32_e32 v38, v37
	v_exp_f32_e32 v39, v39
	v_add_f32_e32 v37, v19, v41
	v_exp_f32_e32 v40, v40
	v_exp_f32_e32 v41, v37
	v_fmac_f32_e32 v14, v20, v38
	v_fmac_f32_e32 v14, v21, v39
	v_fmac_f32_e32 v14, v22, v40
	v_fmac_f32_e32 v14, v23, v41
	s_or_b64 exec, exec, s[2:3]
	s_and_saveexec_b64 s[2:3], s[48:49]
	s_cbranch_execz .LBB0_618
